# grid barrier tail rewritten: XCD-last WG does release + non-returning add(TOP); all WGs poll TOP >= nx*(gen+1); drops TOP return round trip and TOPGEN hop
# baseline (speedup 1.0000x reference)
.LBB0_319:
	s_or_b64 exec, exec, s[2:3]
	v_cvt_f32_u32_e32 v4, v2
	s_waitcnt vmcnt(0)
	v_readfirstlane_b32 s2, v3
	v_sub_u32_e32 v3, 0, v2
	v_rcp_iflag_f32_e32 v4, v4
	v_add_u32_e32 v5, s2, v1
	v_mul_f32_e32 v4, 0x4f7ffffe, v4
	v_cvt_u32_f32_e32 v4, v4
	v_mul_lo_u32 v1, v3, v4
	v_mul_hi_u32 v1, v4, v1
	v_add_u32_e32 v1, v4, v1
	v_mul_hi_u32 v1, v5, v1
	v_mul_lo_u32 v3, v1, v2
	v_sub_u32_e32 v3, v5, v3
	v_add_u32_e32 v4, 1, v1
	v_cmp_ge_u32_e32 vcc, v3, v2
	s_nop 1
	v_cndmask_b32_e32 v1, v1, v4, vcc
	v_sub_u32_e32 v4, v3, v2
	v_cndmask_b32_e32 v3, v3, v4, vcc
	v_add_u32_e32 v4, 1, v1
	v_cmp_ge_u32_e32 vcc, v3, v2
	v_add_u32_e32 v3, 1, v5
	s_nop 0
	v_cndmask_b32_e32 v1, v1, v4, vcc
	v_mul_lo_u32 v4, v2, v1
	v_add_u32_e32 v2, v4, v2
	v_cmp_ne_u32_e32 vcc, v3, v2
	s_waitcnt lgkmcnt(0)
	v_add_u32_e32 v3, 1, v1
	v_mul_lo_u32 v3, v3, v0
	s_cbranch_vccnz .Lxb_poll_0
	buffer_wbl2 sc1
	s_waitcnt vmcnt(0)
	v_readlane_b32 s8, v255, 12
	v_readlane_b32 s9, v255, 13
	s_nop 4
	global_atomic_add v193, v238, s[8:9]
.Lxb_poll_0:
	v_readlane_b32 s8, v255, 12
	v_readlane_b32 s9, v255, 13
	s_nop 4
.Lxb_spin_0:
	global_load_dword v4, v193, s[8:9] sc1
	s_waitcnt vmcnt(0)
	v_cmp_lt_u32_e32 vcc, v4, v3
	s_cbranch_vccz .Lxb_done_0
	s_sleep 1
	s_branch .Lxb_spin_0
.Lxb_done_0:
	buffer_inv sc1
	s_waitcnt vmcnt(0)

.Lxb_done_7:
	buffer_inv sc1
	s_waitcnt vmcnt(0)
	s_branch .LBB0_290
